# GEMM tile head: 32-bit unit index and unsigned shift/magic divisions (17 fewer scalar instructions on the per-tile serial path)
# baseline (speedup 1.0000x reference)
;   __device__ bool next(int i, Unit& u) const {
;     const long L = (long)i * G + c; if (L >= nwg) return false;
;     int wgid = (int)L; { const int q = nwg / NXCD, r = nwg % NXCD, xcd = wgid % NXCD, off = wgid / NXCD; wgid = (xcd < r ? xcd * (q + 1) : r * (q + 1) + (xcd - r) * q) + off; }
;     const int nig = WGM * nN, gid = wgid / nig, fm = gid * WGM, gsz = (nM - fm) < WGM ? (nM - fm) : WGM;
;     u.pm = fm + ((wgid % nig) % gsz); u.pn = (wgid % nig) / gsz; u.swap = (u.pn >= slo && u.pn < shi) ? 1 : 0; return true;
.LBB0_51:
	s_add_i32 s68, s68, 1
	v_readlane_b32 s8, v253, 6
	v_readlane_b32 s0, v253, 9
	s_mov_b64 s[12:13], s[16:17]
	s_mul_i32 s16, s68, s8
	s_add_i32 s16, s16, s0
	s_mov_b64 s[10:11], s[18:19]
	s_mov_b32 s73, s87
	s_mov_b32 s72, s86
	s_mov_b32 s71, s24
	s_cmp_ge_u32 s16, s92
	s_cselect_b64 s[8:9], -1, 0
	s_cselect_b64 s[0:1], 0, -1
	s_cbranch_scc1 .LBB0_53
	s_lshr_b32 s18, s16, 3
	s_and_b32 s16, s16, 7
	s_mul_i32 s16, s81, s16
	s_add_i32 s16, s16, s18
	s_mul_hi_u32 s19, s16, s70
	s_mul_i32 s24, s19, s3
	s_sub_i32 s18, s16, s24
	s_add_i32 s24, s19, 1
	s_sub_i32 s74, s18, s3
	s_cmp_ge_u32 s18, s3
	s_cselect_b32 s19, s24, s19
	s_cselect_b32 s18, s74, s18
	s_add_i32 s24, s19, 1
	s_cmp_ge_u32 s18, s3
	s_cselect_b32 s17, s24, s19
	s_lshl_b32 s18, s17, 3
	s_mul_i32 s17, s17, s80
	s_sub_i32 s16, s16, s17
	s_lshr_b32 s86, s16, 3
	s_and_b32 s16, s16, 7
	s_add_i32 s87, s16, s18
	v_readlane_b32 s16, v254, 37
	v_readlane_b32 s18, v254, 35
	s_cmp_ge_i32 s86, s16
	s_cselect_b32 s16, 1, 0
	s_cmp_lt_i32 s86, s18
	s_cselect_b32 s18, 1, 0
	s_and_b32 s24, s16, s18
